# mixer A: two gather steps in flight (second K/V register set, step loop unrolled by two), first-step index look-ups batched
# speedup vs baseline: 1.1774x; 1.0091x over previous
; DI void lds_fence() { asm volatile("s_waitcnt lgkmcnt(0)" ::: "memory"); __builtin_amdgcn_wave_barrier(); }
; #define A_LOAD(j) do { _Pragma("unroll") for (int i = 0; i < 4; ++i) { const int row = (lane >> 3) + 8 * i, ch = lane & 7, e = 32 * (j) + row; \
;       const int tokk = (e < count) ? (int)sel_l[e] : 0; const size_t off = (size_t)tokk * NPE + ch * 8; R.k[i] = *(const u32x4*)(Kg + off); R.v[i] = *(const u32x4*)(Vg + off); } } while (0)
; DI void mixerA_item(const Params& p, int item, bf16* Ks, bf16* Vs, int lane) {
;     ...
;   const int count = (t + 1 < 256) ? t + 1 : 256, nsteps = (count + 31) >> 5;
;   bf16x8 qf[2];
; #pragma unroll
;   for (int ks = 0; ks < 2; ++ks) qf[ks] = *(const bf16x8*)(PE + (size_t)item * NPE + E_AQ + head * 64 + ks * 32 + qd * 8);
;   f32x4 o[4];
; #pragma unroll
;   for (int d = 0; d < 4; ++d) o[d] = (f32x4){0.f, 0.f, 0.f, 0.f};
;   float m = -1e30f, l = 0.f;
;   const bf16* Kg = PE + rowb * NPE + E_AK; const bf16* Vg = PE + rowb * NPE + E_AV;
;   KVRegs R;
;   unsigned short* sel_l = (unsigned short*)(Vs + 32 * WP);
;   lds_fence();
;   *(u32x2*)(sel_l + 4 * lane) = *(const u32x2*)(SEL + 4 * lane);
;   lds_fence();
;     ...
;   A_LOAD(0);
.LBB0_2146:
	v_readlane_b32 s8, v254, 3
	v_readlane_b32 s9, v254, 4
	s_load_dwordx2 s[6:7], s[8:9], 0x158
	v_and_b32_e32 v0, 4, v73
	v_cmp_eq_u32_e32 vcc, 0, v0
	s_waitcnt lgkmcnt(0)
	v_ashrrev_i32_e32 v1, 2, v73
	v_cndmask_b32_e32 v0, v106, v107, vcc
	s_waitcnt lgkmcnt(0)
	v_mad_u64_u32 v[8:9], s[6:7], v1, s6, v[0:1]
	v_cmp_gt_i32_e32 vcc, s25, v8
	s_and_saveexec_b64 s[20:21], vcc
	s_cbranch_execz .LBB0_2145
	v_lshlrev_b32_e32 v9, 2, v8
	v_or_b32_e32 v82, v9, v103
	v_ashrrev_i32_e32 v83, 31, v82
	v_lshlrev_b64 v[10:11], 9, v[82:83]
	v_mad_i64_i32 v[84:85], s[6:7], v82, s27, v[76:77]
	v_mov_b32_e32 v81, v69
	v_lshl_add_u64 v[12:13], v[84:85], 0, v[80:81]
	v_lshl_add_u64 v[10:11], v[70:71], 0, v[10:11]
	global_load_dwordx4 v[0:3], v[12:13], off
	global_load_dwordx4 v[4:7], v[12:13], off offset:64
	s_waitcnt lgkmcnt(0)
	global_load_dwordx2 v[10:11], v[10:11], off
	v_bitop3_b32 v9, v9, s26, v103 bitop3:0xc8
	v_min_u32_e32 v81, 0xff, v9
	v_cmp_le_u32_e64 s[8:9], v88, v81
	v_cmp_le_u32_e64 s[10:11], v90, v81
	v_cmp_le_u32_e64 s[12:13], v91, v81
	v_cmp_le_u32_e64 s[14:15], v92, v81
	s_waitcnt vmcnt(0)
	ds_write_b64 v75, v[10:11] offset:9216
	s_waitcnt lgkmcnt(0)
	ds_read_u16 v240, v89 offset:9216
	ds_read_u16 v241, v89 offset:9232
	ds_read_u16 v242, v89 offset:9248
	ds_read_u16 v243, v89 offset:9264
	v_ashrrev_i32_e32 v11, 11, v8
	v_mov_b64_e32 v[8:9], s[2:3]
	v_mad_i64_i32 v[86:87], s[6:7], v11, s28, v[8:9]
	s_waitcnt lgkmcnt(0)
	v_mul_u32_u24_e32 v240, 0xc00, v240
	v_mul_u32_u24_e32 v241, 0xc00, v241
	v_mul_u32_u24_e32 v242, 0xc00, v242
	v_mul_u32_u24_e32 v243, 0xc00, v243
	v_cndmask_b32_e64 v240, 0, v240, s[8:9]
	v_cndmask_b32_e64 v241, 0, v241, s[10:11]
	v_cndmask_b32_e64 v242, 0, v242, s[12:13]
	v_cndmask_b32_e64 v243, 0, v243, s[14:15]
	v_or_b32_e32 v240, v240, v72
	v_or_b32_e32 v241, v241, v72
	v_or_b32_e32 v242, v242, v72
	v_or_b32_e32 v243, v243, v72
	v_lshlrev_b32_e32 v68, 1, v240
	v_lshl_add_u64 v[200:201], v[86:87], 0, v[68:69]
	v_lshlrev_b32_e32 v68, 1, v241
	v_lshl_add_u64 v[202:203], v[86:87], 0, v[68:69]
	v_lshlrev_b32_e32 v68, 1, v242
	v_lshl_add_u64 v[204:205], v[86:87], 0, v[68:69]
	v_lshlrev_b32_e32 v68, 1, v243
	v_lshl_add_u64 v[206:207], v[86:87], 0, v[68:69]
	global_load_dwordx4 v[20:23], v[200:201], off offset:1024
	global_load_dwordx4 v[24:27], v[200:201], off offset:1152
	global_load_dwordx4 v[28:31], v[202:203], off offset:1024
	global_load_dwordx4 v[32:35], v[202:203], off offset:1152
	global_load_dwordx4 v[40:43], v[204:205], off offset:1024
	global_load_dwordx4 v[44:47], v[204:205], off offset:1152
	global_load_dwordx4 v[52:55], v[206:207], off offset:1024
	global_load_dwordx4 v[48:51], v[206:207], off offset:1152
	v_add_u32_e32 v8, 32, v81
	v_mov_b32_e32 v109, 0
	v_add_u32_e32 v110, 1, v81
	v_lshrrev_b32_e32 v111, 5, v8
	v_mov_b32_e32 v114, 0xf149f2ca
	s_mov_b32 s31, 0
	s_mov_b64 s[22:23], 0
	v_mov_b32_e32 v112, v105
	v_mov_b32_e32 v113, v104
	v_mov_b32_e32 v36, 0
	v_mov_b32_e32 v37, v109
	v_mov_b32_e32 v38, v109
	v_mov_b32_e32 v39, v109
	v_mov_b32_e32 v8, 0
	v_mov_b32_e32 v9, v109
	v_mov_b32_e32 v10, v109
	v_mov_b32_e32 v11, v109
	v_mov_b32_e32 v12, v109
	v_mov_b32_e32 v13, v109
	v_mov_b32_e32 v14, v109
	v_mov_b32_e32 v15, v109
	v_mov_b32_e32 v16, v109
	v_mov_b32_e32 v17, v109
	v_mov_b32_e32 v18, v109
	v_mov_b32_e32 v19, v109
	v_mov_b32_e32 v56, v109
	v_mov_b32_e32 v57, v109
	v_mov_b32_e32 v58, v109
	v_mov_b32_e32 v59, v109
	v_readfirstlane_b32 s34, v111
	s_cmp_gt_u32 s34, 1
	s_cbranch_scc0 .La2_pro_done
	ds_read_u16 v240, v113
	ds_read_u16 v241, v113 offset:16
	ds_read_u16 v242, v113 offset:32
	ds_read_u16 v243, v113 offset:48
	v_add_u32_e32 v244, -24, v112
	v_add_u32_e32 v245, -16, v112
	v_add_u32_e32 v246, -8, v112
	v_mov_b32_e32 v247, v112
	v_cmp_le_u32_e64 s[8:9], v244, v81
	v_cmp_le_u32_e64 s[10:11], v245, v81
	v_cmp_le_u32_e64 s[12:13], v246, v81
	v_cmp_le_u32_e64 s[14:15], v247, v81
	s_waitcnt lgkmcnt(0)
	v_mul_u32_u24_e32 v240, 0xc00, v240
	v_mul_u32_u24_e32 v241, 0xc00, v241
	v_mul_u32_u24_e32 v242, 0xc00, v242
	v_mul_u32_u24_e32 v243, 0xc00, v243
	v_cndmask_b32_e64 v240, 0, v240, s[8:9]
	v_cndmask_b32_e64 v241, 0, v241, s[10:11]
	v_cndmask_b32_e64 v242, 0, v242, s[12:13]
	v_cndmask_b32_e64 v243, 0, v243, s[14:15]
	v_or_b32_e32 v240, v240, v72
	v_or_b32_e32 v241, v241, v72
	v_or_b32_e32 v242, v242, v72
	v_or_b32_e32 v243, v243, v72
	v_lshlrev_b32_e32 v68, 1, v240
	v_lshl_add_u64 v[200:201], v[86:87], 0, v[68:69]
	v_lshlrev_b32_e32 v68, 1, v241
	v_lshl_add_u64 v[202:203], v[86:87], 0, v[68:69]
	v_lshlrev_b32_e32 v68, 1, v242
	v_lshl_add_u64 v[204:205], v[86:87], 0, v[68:69]
	v_lshlrev_b32_e32 v68, 1, v243
	v_lshl_add_u64 v[206:207], v[86:87], 0, v[68:69]
	global_load_dwordx4 v[208:211], v[200:201], off offset:1024
	global_load_dwordx4 v[212:215], v[200:201], off offset:1152
	global_load_dwordx4 v[216:219], v[202:203], off offset:1024
	global_load_dwordx4 v[220:223], v[202:203], off offset:1152
	global_load_dwordx4 v[224:227], v[204:205], off offset:1024
	global_load_dwordx4 v[228:231], v[204:205], off offset:1152
	global_load_dwordx4 v[232:235], v[206:207], off offset:1024
	global_load_dwordx4 v[236:239], v[206:207], off offset:1152

; DI unsigned cvtpk(float lo, float hi) { f32x2_t v = {lo, hi}; bf16x2_t b = __builtin_convertvector(v, bf16x2_t); return __builtin_bit_cast(unsigned, b); }
; DI float fexp2(float x) { return __builtin_amdgcn_exp2f(x); }
; DI f32x4 mfma16(bf16x8 a, bf16x8 b, f32x4 c) { return __builtin_amdgcn_mfma_f32_16x16x32_bf16(a, b, c, 0, 0, 0); }
; DI s16x4 trread(const bf16* p) { return __builtin_bit_cast(s16x4, __builtin_amdgcn_ds_read_tr16_b64_v4i16((LAS s16x4*)p)); }
; DI void lds_fence() { asm volatile("s_waitcnt lgkmcnt(0)" ::: "memory"); __builtin_amdgcn_wave_barrier(); }
; #define A_LOAD(j) do { _Pragma("unroll") for (int i = 0; i < 4; ++i) { const int row = (lane >> 3) + 8 * i, ch = lane & 7, e = 32 * (j) + row; \
;       const int tokk = (e < count) ? (int)sel_l[e] : 0; const size_t off = (size_t)tokk * NPE + ch * 8; R.k[i] = *(const u32x4*)(Kg + off); R.v[i] = *(const u32x4*)(Vg + off); } } while (0)
; DI void attn_step16(const bf16* Kt, const bf16* Vt, const bf16x8 (&qf)[2], f32x4 (&o)[4], float& m, float& l, int nvalid  , float c2, int lane) {
;     ...
;   const float negm = -m; float ps = 0.f;
; #pragma unroll
;   for (int j = 0; j < 4; ++j) { s0[j] = fexp2(__builtin_fmaf(s0[j], c2, negm)); s1[j] = fexp2(__builtin_fmaf(s1[j], c2, negm)); ps += s0[j] + s1[j]; }
;   l += ps;
;   u32x4 pw; pw.x = cvtpk(s0[0], s0[1]); pw.y = cvtpk(s0[2], s0[3]); pw.z = cvtpk(s1[0], s1[1]); pw.w = cvtpk(s1[2], s1[3]);
;   const bf16x8 pf = __builtin_bit_cast(bf16x8, pw);
;   const int i16 = lane & 15, rq = i16 >> 2, pp = i16 & 3;
; #pragma unroll
;   for (int dt = 0; dt < 4; ++dt) {
;     const s16x4 lo = trread(Vt + (4 * qd + rq) * WP + 16 * dt + 4 * pp);
;     const s16x4 hi = trread(Vt + (16 + 4 * qd + rq) * WP + 16 * dt + 4 * pp);
;     const bf16x8 vf = __builtin_shufflevector(lo, hi, 0, 1, 2, 3, 4, 5, 6, 7);
;     o[dt] = mfma16(vf, pf, o[dt]);
;   }
; }
; DI void mixerA_item(const Params& p, int item, bf16* Ks, bf16* Vs, int lane) {
;     ...
;   for (int j = 0; j < nsteps; ++j) {
;     lds_fence();
;     kv_store(R, Ks, Vs, lane);
;     lds_fence();
;     if (j + 1 < nsteps) A_LOAD(j + 1);
.LBB0_2156:
	s_or_b64 vcc, s[10:11], s[16:17]
	v_cndmask_b32_e32 v36, v120, v61, vcc
	s_or_b64 vcc, vcc, s[6:7]
	v_cndmask_b32_e32 v37, v117, v60, vcc
	s_or_b64 vcc, s[12:13], s[14:15]
	v_cndmask_b32_e32 v38, v121, v65, vcc
	s_or_b64 vcc, vcc, s[8:9]
	v_cndmask_b32_e32 v39, v68, v64, vcc
	v_fma_f32 v37, v37, s30, -v114
	v_exp_f32_e32 v65, v37
	v_fma_f32 v37, v39, s30, -v114
	v_fma_f32 v36, v36, s30, -v114
	v_exp_f32_e32 v120, v37
	v_exp_f32_e32 v68, v36
	v_fma_f32 v36, v38, s30, -v114
	v_exp_f32_e32 v38, v36
	v_add_f32_e32 v39, v120, v65
	v_cndmask_b32_e64 v62, v118, v62, s[10:11]
	v_cndmask_b32_e64 v64, v119, v66, s[12:13]
	v_pk_add_f32 v[36:37], v[38:39], v[68:69]
	v_cvt_pk_bf16_f32 v38, v120, v38
	v_pk_add_f32 v[60:61], v[36:37], v[36:37] op_sel_hi:[0,1]
	v_fma_f32 v36, v62, s30, -v114
	v_exp_f32_e32 v62, v36
	v_fma_f32 v36, v64, s30, -v114
	v_exp_f32_e32 v66, v36
	v_fma_f32 v36, v115, s30, -v114
	v_exp_f32_e32 v60, v36
	v_fma_f32 v36, v116, s30, -v114
	v_exp_f32_e32 v64, v36
	ds_read_b64_tr_b16 v[118:119], v102 offset:6912
	ds_read_b64_tr_b16 v[116:117], v102 offset:4608
	ds_read_b64_tr_b16 v[122:123], v102 offset:6944
	ds_read_b64_tr_b16 v[120:121], v102 offset:4640
	ds_read_b64_tr_b16 v[124:125], v102 offset:4672
	ds_read_b64_tr_b16 v[128:129], v102 offset:4704
	ds_read_b64_tr_b16 v[126:127], v102 offset:6976
	ds_read_b64_tr_b16 v[130:131], v102 offset:7008
	v_cvt_pk_bf16_f32 v36, v65, v68
	v_cvt_pk_bf16_f32 v37, v62, v60
	v_cvt_pk_bf16_f32 v39, v66, v64
	v_add_f32_e32 v65, v66, v62
	v_pk_add_f32 v[60:61], v[64:65], v[60:61]
	s_waitcnt lgkmcnt(6)
	v_mfma_f32_16x16x32_bf16 v[8:11], v[116:119], v[36:39], v[8:11]
	v_add_f32_e32 v60, v60, v61
	v_cmp_eq_u32_e32 vcc, s31, v111
	v_add_f32_e32 v109, v109, v60
	s_waitcnt lgkmcnt(4)
	v_mfma_f32_16x16x32_bf16 v[12:15], v[120:123], v[36:39], v[12:15]
	v_subrev_u32_e32 v110, 32, v110
	v_add_u32_e32 v113, 64, v113
	v_add_u32_e32 v112, 32, v112
	s_waitcnt lgkmcnt(1)
	v_mfma_f32_16x16x32_bf16 v[16:19], v[124:127], v[36:39], v[16:19]
	s_or_b64 s[22:23], vcc, s[22:23]
	s_waitcnt lgkmcnt(0)
	v_mfma_f32_16x16x32_bf16 v[36:39], v[128:131], v[36:39], v[56:59]
	s_nop 7
	v_mov_b32_e32 v56, v36
	v_mov_b32_e32 v57, v37
	v_mov_b32_e32 v58, v38
	v_mov_b32_e32 v59, v39
	s_andn2_b64 exec, exec, s[22:23]
	s_cbranch_execz .LBB0_2169
	s_branch .La2_headB
.LBB0_2157:
	s_waitcnt lgkmcnt(0)
	s_add_i32 s35, s31, 1
	s_cmp_lt_u32 s35, s34
	s_cbranch_scc0 .La2_w0A
	s_waitcnt vmcnt(8)
	s_branch .La2_w1A

; DI float fexp2(float x) { return __builtin_amdgcn_exp2f(x); }
; DI f32x4 mfma16(bf16x8 a, bf16x8 b, f32x4 c) { return __builtin_amdgcn_mfma_f32_16x16x32_bf16(a, b, c, 0, 0, 0); }
; DI void lds_fence() { asm volatile("s_waitcnt lgkmcnt(0)" ::: "memory"); __builtin_amdgcn_wave_barrier(); }
; DI float half_max(float v) { auto rr = __builtin_amdgcn_permlane32_swap(__float_as_uint(v), __float_as_uint(v), false, false); return fmaxf(__uint_as_float(rr[0]), __uint_as_float(rr[1])); }
; #define A_LOAD(j) do { _Pragma("unroll") for (int i = 0; i < 4; ++i) { const int row = (lane >> 3) + 8 * i, ch = lane & 7, e = 32 * (j) + row; \
;       const int tokk = (e < count) ? (int)sel_l[e] : 0; const size_t off = (size_t)tokk * NPE + ch * 8; R.k[i] = *(const u32x4*)(Kg + off); R.v[i] = *(const u32x4*)(Vg + off); } } while (0)
; DI void attn_step16(const bf16* Kt, const bf16* Vt, const bf16x8 (&qf)[2], f32x4 (&o)[4], float& m, float& l, int nvalid  , float c2, int lane) {
;     ...
;   f32x4 s0 = {0.f, 0.f, 0.f, 0.f}, s1 = {0.f, 0.f, 0.f, 0.f};
; #pragma unroll
;   for (int ks = 0; ks < 2; ++ks) {
;     const bf16x8 k0 = *(const bf16x8*)(Kt + c * WP + ks * 32 + qd * 8);
;     const bf16x8 k1 = *(const bf16x8*)(Kt + (16 + c) * WP + ks * 32 + qd * 8);
;     s0 = mfma16(k0, qf[ks], s0); s1 = mfma16(k1, qf[ks], s1);
;   }
;   float mx = -INFINITY;
; #pragma unroll
;   for (int j = 0; j < 4; ++j) { if (4 * qd + j >= nvalid) s0[j] = -INFINITY; if (16 + 4 * qd + j >= nvalid) s1[j] = -INFINITY; mx = fmaxf(mx, fmaxf(s0[j], s1[j])); }
;   mx = fmaxf(mx, __shfl_xor(mx, 16)); mx = half_max(mx);
;   const float mxs = mx * c2;
;   if (__any(mxs > m + 6.f)) {
;     const float mn = fmaxf(m, mxs); const float alpha = fexp2(m - mn); l *= alpha;
; #pragma unroll
;     for (int d = 0; d < 4; ++d) o[d] = o[d] * alpha;
;     m = mn;
;   }
; DI void mixerA_item(const Params& p, int item, bf16* Ks, bf16* Vs, int lane) {
;     ...
;   for (int j = 0; j < nsteps; ++j) {
;     lds_fence();
;     kv_store(R, Ks, Vs, lane);
;     lds_fence();
;     if (j + 1 < nsteps) A_LOAD(j + 1);
.La2_w1A:
	ds_write_b128 v93, v[20:23]
	ds_write_b128 v93, v[24:27] offset:4608
	ds_write_b128 v93, v[28:31] offset:1152
	ds_write_b128 v93, v[32:35] offset:5760
	ds_write_b128 v93, v[40:43] offset:2304
	ds_write_b128 v93, v[44:47] offset:6912
	ds_write_b128 v93, v[52:55] offset:3456
	ds_write_b128 v93, v[48:51] offset:8064
	s_waitcnt lgkmcnt(0)
	s_add_i32 s31, s31, 1
	s_add_i32 s35, s31, 1
	s_cmp_lt_u32 s35, s34
	s_cbranch_scc0 .LBB0_2167
	ds_read_u16 v240, v113 offset:64
	ds_read_u16 v241, v113 offset:80
	ds_read_u16 v242, v113 offset:96
	ds_read_u16 v243, v113 offset:112
	v_add_u32_e32 v244, 8, v112
	v_add_u32_e32 v245, 16, v112
	v_add_u32_e32 v246, 24, v112
	v_add_u32_e32 v247, 32, v112
	v_cmp_le_u32_e64 s[8:9], v244, v81
	v_cmp_le_u32_e64 s[10:11], v245, v81
	v_cmp_le_u32_e64 s[12:13], v246, v81
	v_cmp_le_u32_e64 s[14:15], v247, v81
	s_waitcnt lgkmcnt(0)
	v_mul_u32_u24_e32 v240, 0xc00, v240
	v_mul_u32_u24_e32 v241, 0xc00, v241
	v_mul_u32_u24_e32 v242, 0xc00, v242
	v_mul_u32_u24_e32 v243, 0xc00, v243
	v_cndmask_b32_e64 v240, 0, v240, s[8:9]
	v_cndmask_b32_e64 v241, 0, v241, s[10:11]
	v_cndmask_b32_e64 v242, 0, v242, s[12:13]
	v_cndmask_b32_e64 v243, 0, v243, s[14:15]
	v_or_b32_e32 v240, v240, v72
	v_or_b32_e32 v241, v241, v72
	v_or_b32_e32 v242, v242, v72
	v_or_b32_e32 v243, v243, v72
	v_lshlrev_b32_e32 v68, 1, v240
	v_lshl_add_u64 v[200:201], v[86:87], 0, v[68:69]
	v_lshlrev_b32_e32 v68, 1, v241
	v_lshl_add_u64 v[202:203], v[86:87], 0, v[68:69]
	v_lshlrev_b32_e32 v68, 1, v242
	v_lshl_add_u64 v[204:205], v[86:87], 0, v[68:69]
	v_lshlrev_b32_e32 v68, 1, v243
	v_lshl_add_u64 v[206:207], v[86:87], 0, v[68:69]
	global_load_dwordx4 v[20:23], v[200:201], off offset:1024
	global_load_dwordx4 v[24:27], v[200:201], off offset:1152
	global_load_dwordx4 v[28:31], v[202:203], off offset:1024
	global_load_dwordx4 v[32:35], v[202:203], off offset:1152
	global_load_dwordx4 v[40:43], v[204:205], off offset:1024
	global_load_dwordx4 v[44:47], v[204:205], off offset:1152
	global_load_dwordx4 v[52:55], v[206:207], off offset:1024
	global_load_dwordx4 v[48:51], v[206:207], off offset:1152
.LBB0_2167:
	ds_read_b128 v[60:63], v94
	ds_read_b128 v[64:67], v94 offset:64
	ds_read_b128 v[116:119], v94 offset:2304
	ds_read_b128 v[120:123], v94 offset:2368
	v_mov_b32_e32 v68, s29
	v_cmp_lt_i32_e32 vcc, v74, v110
	s_waitcnt lgkmcnt(3)
	v_mfma_f32_16x16x32_bf16 v[60:63], v[60:63], v[0:3], 0
	v_mov_b32_e32 v124, s29
	v_cmp_lt_i32_e64 s[6:7], v96, v110
	v_cmp_lt_i32_e64 s[8:9], v97, v110
	s_waitcnt lgkmcnt(1)
	v_mfma_f32_16x16x32_bf16 v[116:119], v[116:119], v[0:3], 0
	v_cmp_lt_i32_e64 s[16:17], v98, v110
	v_cmp_lt_i32_e64 s[14:15], v99, v110
	v_cmp_lt_i32_e64 s[10:11], v100, v110
	v_mfma_f32_16x16x32_bf16 v[60:63], v[64:67], v[4:7], v[60:63]
	v_cmp_lt_i32_e64 s[12:13], v101, v110
	s_waitcnt lgkmcnt(0)
	v_mfma_f32_16x16x32_bf16 v[64:67], v[120:123], v[4:7], v[116:119]
	s_nop 4
	v_cndmask_b32_e32 v117, v68, v60, vcc
	v_cmp_lt_i32_e32 vcc, v95, v110
	v_cndmask_b32_e64 v120, v108, v61, s[6:7]
	v_max_f32_e32 v116, v117, v117
	v_cndmask_b32_e32 v68, v124, v64, vcc
	v_max_f32_e32 v115, v68, v68
	v_cndmask_b32_e64 v121, v108, v65, s[8:9]
	v_max_f32_e32 v115, v116, v115
	v_max_f32_e32 v116, v121, v121
	v_max_f32_e32 v118, v120, v120
	v_max_f32_e32 v116, v118, v116
	v_cndmask_b32_e64 v118, v108, v62, s[16:17]
	v_cndmask_b32_e64 v119, v108, v66, s[14:15]
	v_max3_f32 v122, v115, s29, v116
	v_max_f32_e32 v115, v119, v119
	v_max_f32_e32 v116, v118, v118
	v_max_f32_e32 v123, v116, v115
	v_cndmask_b32_e64 v115, v108, v63, s[10:11]
	v_cndmask_b32_e64 v116, v108, v67, s[12:13]
	v_max_f32_e32 v63, v116, v116
	v_max_f32_e32 v67, v115, v115
	v_max_f32_e32 v63, v67, v63
	v_max3_f32 v122, v122, v123, v63
	v_and_b32_e32 v63, 64, v183
	v_xor_b32_e32 v67, 16, v183
	v_add_u32_e32 v63, 64, v63
	v_cmp_lt_i32_e32 vcc, v67, v63
	s_nop 1
	v_cndmask_b32_e32 v67, v183, v67, vcc
	v_lshlrev_b32_e32 v67, 2, v67
	v_mov_b32_e32 v123, v122
	s_nop 1
	v_permlane16_swap_b32_e32 v122, v123
	v_max_f32_e32 v122, v122, v123
	v_mov_b32_e32 v123, v122
	s_nop 1
	v_permlane32_swap_b32_e32 v122, v123
	v_max_f32_e32 v123, v123, v123
	v_max_f32_e32 v122, v122, v122
	v_max_f32_e32 v122, v122, v123
	v_mul_f32_e32 v122, 0x3e38aa3b, v122
	v_add_f32_e32 v123, 0x40c00000, v114
	v_cmp_gt_f32_e32 vcc, v122, v123
	s_cbranch_vccz .LBB0_2156
	v_max_f32_e32 v56, v122, v122
	v_max_f32_e32 v57, v114, v114
	v_max_f32_e32 v122, v57, v56
	v_sub_f32_e32 v56, v114, v122
	v_exp_f32_e32 v58, v56
	v_mov_b32_e32 v114, v122
	v_mul_f32_e32 v109, v109, v58
	v_pk_mul_f32 v[18:19], v[18:19], v[58:59] op_sel_hi:[1,0]
	v_pk_mul_f32 v[16:17], v[16:17], v[58:59] op_sel_hi:[1,0]
	v_pk_mul_f32 v[14:15], v[14:15], v[58:59] op_sel_hi:[1,0]
	v_pk_mul_f32 v[12:13], v[12:13], v[58:59] op_sel_hi:[1,0]
	v_pk_mul_f32 v[10:11], v[10:11], v[58:59] op_sel_hi:[1,0]
	v_pk_mul_f32 v[8:9], v[8:9], v[58:59] op_sel_hi:[1,0]
	v_pk_mul_f32 v[56:57], v[36:37], v[58:59] op_sel_hi:[1,0]
	v_pk_mul_f32 v[58:59], v[38:39], v[58:59] op_sel_hi:[1,0]
	s_branch .LBB0_2156

; DI void lds_fence() { asm volatile("s_waitcnt lgkmcnt(0)" ::: "memory"); __builtin_amdgcn_wave_barrier(); }
; #define A_LOAD(j) do { _Pragma("unroll") for (int i = 0; i < 4; ++i) { const int row = (lane >> 3) + 8 * i, ch = lane & 7, e = 32 * (j) + row; \
;       const int tokk = (e < count) ? (int)sel_l[e] : 0; const size_t off = (size_t)tokk * NPE + ch * 8; R.k[i] = *(const u32x4*)(Kg + off); R.v[i] = *(const u32x4*)(Vg + off); } } while (0)
; DI void mixerA_item(const Params& p, int item, bf16* Ks, bf16* Vs, int lane) {
;     ...
;   for (int j = 0; j < nsteps; ++j) {
;     lds_fence();
;     kv_store(R, Ks, Vs, lane);
;     lds_fence();
;     if (j + 1 < nsteps) A_LOAD(j + 1);
.La2_w1B:
	ds_write_b128 v93, v[208:211]
	ds_write_b128 v93, v[212:215] offset:4608
	ds_write_b128 v93, v[216:219] offset:1152
	ds_write_b128 v93, v[220:223] offset:5760
	ds_write_b128 v93, v[224:227] offset:2304
	ds_write_b128 v93, v[228:231] offset:6912
	ds_write_b128 v93, v[232:235] offset:3456
	ds_write_b128 v93, v[236:239] offset:8064
	s_waitcnt lgkmcnt(0)
	s_add_i32 s31, s31, 1
	s_add_i32 s35, s31, 1
	s_cmp_lt_u32 s35, s34
	s_cbranch_scc0 .La2_2167B
	ds_read_u16 v240, v113 offset:64
	ds_read_u16 v241, v113 offset:80
	ds_read_u16 v242, v113 offset:96
	ds_read_u16 v243, v113 offset:112
	v_add_u32_e32 v244, 8, v112
	v_add_u32_e32 v245, 16, v112
	v_add_u32_e32 v246, 24, v112
	v_add_u32_e32 v247, 32, v112
	v_cmp_le_u32_e64 s[8:9], v244, v81
	v_cmp_le_u32_e64 s[10:11], v245, v81
	v_cmp_le_u32_e64 s[12:13], v246, v81
	v_cmp_le_u32_e64 s[14:15], v247, v81
	s_waitcnt lgkmcnt(0)
	v_mul_u32_u24_e32 v240, 0xc00, v240
	v_mul_u32_u24_e32 v241, 0xc00, v241
	v_mul_u32_u24_e32 v242, 0xc00, v242
	v_mul_u32_u24_e32 v243, 0xc00, v243
	v_cndmask_b32_e64 v240, 0, v240, s[8:9]
	v_cndmask_b32_e64 v241, 0, v241, s[10:11]
	v_cndmask_b32_e64 v242, 0, v242, s[12:13]
	v_cndmask_b32_e64 v243, 0, v243, s[14:15]
	v_or_b32_e32 v240, v240, v72
	v_or_b32_e32 v241, v241, v72
	v_or_b32_e32 v242, v242, v72
	v_or_b32_e32 v243, v243, v72
	v_lshlrev_b32_e32 v68, 1, v240
	v_lshl_add_u64 v[200:201], v[86:87], 0, v[68:69]
	v_lshlrev_b32_e32 v68, 1, v241
	v_lshl_add_u64 v[202:203], v[86:87], 0, v[68:69]
	v_lshlrev_b32_e32 v68, 1, v242
	v_lshl_add_u64 v[204:205], v[86:87], 0, v[68:69]
	v_lshlrev_b32_e32 v68, 1, v243
	v_lshl_add_u64 v[206:207], v[86:87], 0, v[68:69]
	global_load_dwordx4 v[208:211], v[200:201], off offset:1024
	global_load_dwordx4 v[212:215], v[200:201], off offset:1152
	global_load_dwordx4 v[216:219], v[202:203], off offset:1024
	global_load_dwordx4 v[220:223], v[202:203], off offset:1152
	global_load_dwordx4 v[224:227], v[204:205], off offset:1024
	global_load_dwordx4 v[228:231], v[204:205], off offset:1152
	global_load_dwordx4 v[232:235], v[206:207], off offset:1024
	global_load_dwordx4 v[236:239], v[206:207], off offset:1152
